# attn_d epilogue gain loads hoisted; mlstm_a3 forward C-state fragment loads issued in two waves
# baseline (speedup 1.0000x reference)
.LBB0_634:
	s_setprio 0
	global_load_dword v2, v1, s[0:1]
	v_and_b32_e32 v4, 64, v198
	v_xor_b32_e32 v3, 16, v198
	v_add_u32_e32 v4, 64, v4
	v_cmp_lt_i32_e32 vcc, v3, v4
	v_xor_b32_e32 v5, 32, v198
	s_nop 0
	v_cndmask_b32_e32 v3, v198, v3, vcc
	v_lshlrev_b32_e32 v88, 2, v3
	ds_bpermute_b32 v3, v88, v0
	v_cmp_lt_i32_e32 vcc, v5, v4
	s_waitcnt lgkmcnt(0)
	v_add_f32_e32 v0, v0, v3
	v_cndmask_b32_e32 v4, v198, v5, vcc
	v_lshlrev_b32_e32 v89, 2, v4
	ds_bpermute_b32 v3, v89, v0
	ds_bpermute_b32 v4, v88, v151
	s_waitcnt lgkmcnt(1)
	v_add_f32_e32 v0, v0, v3
	s_waitcnt lgkmcnt(0)
	v_add_f32_e32 v4, v151, v4
	v_div_scale_f32 v3, s[4:5], v0, v0, 1.0
	ds_bpermute_b32 v5, v89, v4
	v_rcp_f32_e32 v6, v3
	s_waitcnt lgkmcnt(0)
	v_add_f32_e32 v4, v4, v5
	v_fma_f32 v7, -v3, v6, 1.0
	v_div_scale_f32 v5, vcc, 1.0, v0, 1.0
	v_fmac_f32_e32 v6, v7, v6
	v_mul_f32_e32 v7, v5, v6
	v_fma_f32 v8, -v3, v7, v5
	v_fmac_f32_e32 v7, v8, v6
	v_fma_f32 v3, -v3, v7, v5
	v_div_fmas_f32 v3, v3, v6, v7
	v_div_fixup_f32 v0, v3, v0, 1.0
	s_waitcnt vmcnt(0)
	v_div_scale_f32 v5, s[4:5], v4, v4, v2
	v_rcp_f32_e32 v6, v5
	v_div_scale_f32 v3, vcc, v2, v4, v2
	v_fma_f32 v7, -v5, v6, 1.0
	v_fmac_f32_e32 v6, v7, v6
	v_mul_f32_e32 v7, v3, v6
	v_fma_f32 v8, -v5, v7, v3
	v_fmac_f32_e32 v7, v8, v6
	v_fma_f32 v3, -v5, v7, v3
	v_div_fmas_f32 v3, v3, v6, v7
	v_div_fixup_f32 v2, v3, v4, v2
	v_pk_mul_f32 v[4:5], v[36:37], v[2:3] op_sel_hi:[1,0]
	v_pk_mul_f32 v[6:7], v[38:39], v[2:3] op_sel_hi:[1,0]
	v_pk_mul_f32 v[10:11], v[46:47], v[2:3] op_sel_hi:[1,0]
	v_pk_fma_f32 v[38:39], v[28:29], v[0:1], v[4:5] op_sel_hi:[1,0,1] neg_lo:[0,0,1] neg_hi:[0,0,1]
	v_pk_mul_f32 v[8:9], v[44:45], v[2:3] op_sel_hi:[1,0]
	v_pk_mul_f32 v[12:13], v[48:49], v[2:3] op_sel_hi:[1,0]
	v_pk_mul_f32 v[14:15], v[50:51], v[2:3] op_sel_hi:[1,0]
	v_pk_mul_f32 v[16:17], v[60:61], v[2:3] op_sel_hi:[1,0]
	v_pk_mul_f32 v[18:19], v[62:63], v[2:3] op_sel_hi:[1,0]
	v_pk_mul_f32 v[44:45], v[68:69], v[2:3] op_sel_hi:[1,0]
	v_pk_mul_f32 v[46:47], v[70:71], v[2:3] op_sel_hi:[1,0]
	v_pk_mul_f32 v[48:49], v[76:77], v[2:3] op_sel_hi:[1,0]
	v_pk_mul_f32 v[50:51], v[78:79], v[2:3] op_sel_hi:[1,0]
	v_pk_mul_f32 v[60:61], v[80:81], v[2:3] op_sel_hi:[1,0]
	v_pk_mul_f32 v[62:63], v[82:83], v[2:3] op_sel_hi:[1,0]
	v_pk_mul_f32 v[68:69], v[20:21], v[2:3] op_sel_hi:[1,0]
	v_pk_mul_f32 v[2:3], v[22:23], v[2:3] op_sel_hi:[1,0]
	v_pk_fma_f32 v[36:37], v[30:31], v[0:1], v[6:7] op_sel_hi:[1,0,1] neg_lo:[0,0,1] neg_hi:[0,0,1]
	v_pk_fma_f32 v[28:29], v[34:35], v[0:1], v[10:11] op_sel_hi:[1,0,1] neg_lo:[0,0,1] neg_hi:[0,0,1]
	v_pk_mul_f32 v[10:11], v[38:39], v[38:39]
	v_pk_fma_f32 v[30:31], v[32:33], v[0:1], v[8:9] op_sel_hi:[1,0,1] neg_lo:[0,0,1] neg_hi:[0,0,1]
	v_pk_fma_f32 v[26:27], v[40:41], v[0:1], v[12:13] op_sel_hi:[1,0,1] neg_lo:[0,0,1] neg_hi:[0,0,1]
	v_pk_fma_f32 v[24:25], v[42:43], v[0:1], v[14:15] op_sel_hi:[1,0,1] neg_lo:[0,0,1] neg_hi:[0,0,1]
	v_pk_fma_f32 v[22:23], v[52:53], v[0:1], v[16:17] op_sel_hi:[1,0,1] neg_lo:[0,0,1] neg_hi:[0,0,1]
	v_pk_fma_f32 v[20:21], v[54:55], v[0:1], v[18:19] op_sel_hi:[1,0,1] neg_lo:[0,0,1] neg_hi:[0,0,1]
	v_pk_fma_f32 v[18:19], v[56:57], v[0:1], v[44:45] op_sel_hi:[1,0,1] neg_lo:[0,0,1] neg_hi:[0,0,1]
	v_pk_fma_f32 v[16:17], v[58:59], v[0:1], v[46:47] op_sel_hi:[1,0,1] neg_lo:[0,0,1] neg_hi:[0,0,1]
	v_pk_fma_f32 v[14:15], v[64:65], v[0:1], v[48:49] op_sel_hi:[1,0,1] neg_lo:[0,0,1] neg_hi:[0,0,1]
	v_pk_fma_f32 v[12:13], v[66:67], v[0:1], v[50:51] op_sel_hi:[1,0,1] neg_lo:[0,0,1] neg_hi:[0,0,1]
	v_pk_fma_f32 v[8:9], v[72:73], v[0:1], v[60:61] op_sel_hi:[1,0,1] neg_lo:[0,0,1] neg_hi:[0,0,1]
	v_pk_fma_f32 v[6:7], v[74:75], v[0:1], v[62:63] op_sel_hi:[1,0,1] neg_lo:[0,0,1] neg_hi:[0,0,1]
	v_pk_fma_f32 v[4:5], v[84:85], v[0:1], v[68:69] op_sel_hi:[1,0,1] neg_lo:[0,0,1] neg_hi:[0,0,1]
	v_pk_fma_f32 v[2:3], v[86:87], v[0:1], v[2:3] op_sel_hi:[1,0,1] neg_lo:[0,0,1] neg_hi:[0,0,1]
	v_pk_mul_f32 v[32:33], v[36:37], v[36:37]
	v_add_f32_e32 v0, v10, v11
	v_add_f32_e32 v0, v32, v0
	v_pk_mul_f32 v[34:35], v[30:31], v[30:31]
	v_add_f32_e32 v0, v33, v0
	v_add_f32_e32 v0, v34, v0
	v_pk_mul_f32 v[40:41], v[28:29], v[28:29]
	v_add_f32_e32 v0, v35, v0
	v_add_f32_e32 v0, v40, v0
	v_pk_mul_f32 v[42:43], v[26:27], v[26:27]
	v_add_f32_e32 v0, v41, v0
	v_add_f32_e32 v0, v42, v0
	v_pk_mul_f32 v[44:45], v[24:25], v[24:25]
	v_add_f32_e32 v0, v43, v0
	v_add_f32_e32 v0, v44, v0
	v_pk_mul_f32 v[46:47], v[22:23], v[22:23]
	v_add_f32_e32 v0, v45, v0
	v_add_f32_e32 v0, v46, v0
	v_pk_mul_f32 v[48:49], v[20:21], v[20:21]
	v_add_f32_e32 v0, v47, v0
	v_add_f32_e32 v0, v48, v0
	v_pk_mul_f32 v[50:51], v[18:19], v[18:19]
	v_add_f32_e32 v0, v49, v0
	v_add_f32_e32 v0, v50, v0
	v_pk_mul_f32 v[52:53], v[16:17], v[16:17]
	v_add_f32_e32 v0, v51, v0
	v_add_f32_e32 v0, v52, v0
	v_pk_mul_f32 v[54:55], v[14:15], v[14:15]
	v_add_f32_e32 v0, v53, v0
	v_add_f32_e32 v0, v54, v0
	v_pk_mul_f32 v[56:57], v[12:13], v[12:13]
	v_add_f32_e32 v0, v55, v0
	v_add_f32_e32 v0, v56, v0
	v_pk_mul_f32 v[58:59], v[8:9], v[8:9]
	v_add_f32_e32 v0, v57, v0
	v_add_f32_e32 v0, v58, v0
	v_pk_mul_f32 v[60:61], v[6:7], v[6:7]
	v_add_f32_e32 v0, v59, v0
	v_add_f32_e32 v0, v60, v0
	v_pk_mul_f32 v[62:63], v[4:5], v[4:5]
	v_add_f32_e32 v0, v61, v0
	v_add_f32_e32 v0, v62, v0
	v_pk_mul_f32 v[64:65], v[2:3], v[2:3]
	v_add_f32_e32 v0, v63, v0
	v_add_f32_e32 v0, v64, v0
	v_add_f32_e32 v0, v65, v0
	ds_bpermute_b32 v10, v88, v0
	s_andn2_b64 vcc, exec, s[6:7]
	s_waitcnt lgkmcnt(0)
	v_add_f32_e32 v32, v0, v10
	ds_bpermute_b32 v33, v89, v32
	s_cbranch_vccnz .LBB0_607
	v_lshlrev_b32_e32 v0, 1, v167
	v_lshl_add_u64 v[10:11], v[132:133], 0, v[0:1]
	s_waitcnt lgkmcnt(0)
	v_add_f32_e32 v0, v32, v33
	v_fmamk_f32 v0, v0, 0x3c000000, v194
	v_cmp_gt_f32_e32 vcc, s76, v0
	v_mul_f32_e32 v32, 0x4b800000, v0
	v_lshlrev_b32_e32 v40, 2, v167
	global_load_dwordx4 v[212:215], v40, s[36:37]
	global_load_dwordx4 v[216:219], v40, s[36:37] offset:64
	global_load_dwordx4 v[220:223], v40, s[36:37] offset:128
	global_load_dwordx4 v[224:227], v40, s[36:37] offset:192
	global_load_dwordx4 v[228:231], v40, s[36:37] offset:256
	global_load_dwordx4 v[232:235], v40, s[36:37] offset:320
	global_load_dwordx4 v[236:239], v40, s[36:37] offset:384
	global_load_dwordx4 v[240:243], v40, s[36:37] offset:448
	v_cndmask_b32_e32 v0, v0, v32, vcc
	v_rsq_f32_e32 v0, v0
	s_nop 0
	v_mul_f32_e32 v32, 0x45800000, v0
	v_cndmask_b32_e32 v0, v0, v32, vcc
	v_mul_f32_e32 v0, v166, v0
	v_pk_mul_f32 v[38:39], v[38:39], v[0:1] op_sel_hi:[1,0]
	v_pk_mul_f32 v[36:37], v[36:37], v[0:1] op_sel_hi:[1,0]
	v_pk_mul_f32 v[30:31], v[30:31], v[0:1] op_sel_hi:[1,0]
	v_pk_mul_f32 v[28:29], v[28:29], v[0:1] op_sel_hi:[1,0]
	v_pk_mul_f32 v[26:27], v[26:27], v[0:1] op_sel_hi:[1,0]
	v_pk_mul_f32 v[24:25], v[24:25], v[0:1] op_sel_hi:[1,0]
	v_pk_mul_f32 v[22:23], v[22:23], v[0:1] op_sel_hi:[1,0]
	v_pk_mul_f32 v[20:21], v[20:21], v[0:1] op_sel_hi:[1,0]
	v_pk_mul_f32 v[18:19], v[18:19], v[0:1] op_sel_hi:[1,0]
	v_pk_mul_f32 v[16:17], v[16:17], v[0:1] op_sel_hi:[1,0]
	v_pk_mul_f32 v[14:15], v[14:15], v[0:1] op_sel_hi:[1,0]
	v_pk_mul_f32 v[12:13], v[12:13], v[0:1] op_sel_hi:[1,0]
	v_pk_mul_f32 v[8:9], v[8:9], v[0:1] op_sel_hi:[1,0]
	v_pk_mul_f32 v[6:7], v[6:7], v[0:1] op_sel_hi:[1,0]
	v_pk_mul_f32 v[4:5], v[4:5], v[0:1] op_sel_hi:[1,0]
	v_pk_mul_f32 v[2:3], v[2:3], v[0:1] op_sel_hi:[1,0]
	s_waitcnt vmcnt(7)
	v_pk_mul_f32 v[32:33], v[38:39], v[212:213]
	v_pk_mul_f32 v[34:35], v[36:37], v[214:215]
	v_cvt_pk_bf16_f32 v32, v32, v33
	v_cvt_pk_bf16_f32 v33, v34, v35
	global_store_dwordx2 v[10:11], v[32:33], off
	s_waitcnt vmcnt(7)
	v_pk_mul_f32 v[30:31], v[30:31], v[216:217]
	v_pk_mul_f32 v[28:29], v[28:29], v[218:219]
	v_cvt_pk_bf16_f32 v30, v30, v31
	v_cvt_pk_bf16_f32 v31, v28, v29
	global_store_dwordx2 v[10:11], v[30:31], off offset:32
	s_waitcnt vmcnt(7)
	v_pk_mul_f32 v[26:27], v[26:27], v[220:221]
	v_pk_mul_f32 v[24:25], v[24:25], v[222:223]
	v_cvt_pk_bf16_f32 v26, v26, v27
	v_cvt_pk_bf16_f32 v27, v24, v25
	global_store_dwordx2 v[10:11], v[26:27], off offset:64
	s_waitcnt vmcnt(7)
	v_pk_mul_f32 v[22:23], v[22:23], v[224:225]
	v_pk_mul_f32 v[20:21], v[20:21], v[226:227]
	v_cvt_pk_bf16_f32 v22, v22, v23
	v_cvt_pk_bf16_f32 v23, v20, v21
	global_store_dwordx2 v[10:11], v[22:23], off offset:96
	s_waitcnt vmcnt(7)
	v_pk_mul_f32 v[18:19], v[18:19], v[228:229]
	v_pk_mul_f32 v[16:17], v[16:17], v[230:231]
	v_cvt_pk_bf16_f32 v18, v18, v19
	v_cvt_pk_bf16_f32 v19, v16, v17
	global_store_dwordx2 v[10:11], v[18:19], off offset:128
	s_waitcnt vmcnt(7)
	v_pk_mul_f32 v[14:15], v[14:15], v[232:233]
	v_pk_mul_f32 v[12:13], v[12:13], v[234:235]
	v_cvt_pk_bf16_f32 v14, v14, v15
	v_cvt_pk_bf16_f32 v15, v12, v13
	global_store_dwordx2 v[10:11], v[14:15], off offset:160
	s_waitcnt vmcnt(7)
	v_pk_mul_f32 v[8:9], v[8:9], v[236:237]
	v_pk_mul_f32 v[6:7], v[6:7], v[238:239]
	v_cvt_pk_bf16_f32 v8, v8, v9
	v_cvt_pk_bf16_f32 v9, v6, v7
	global_store_dwordx2 v[10:11], v[8:9], off offset:192
	s_waitcnt vmcnt(7)
	v_pk_mul_f32 v[4:5], v[4:5], v[240:241]
	v_pk_mul_f32 v[2:3], v[2:3], v[242:243]
	v_cvt_pk_bf16_f32 v4, v4, v5
	v_cvt_pk_bf16_f32 v5, v2, v3
	global_store_dwordx2 v[10:11], v[4:5], off offset:224
	s_branch .LBB0_607

.LBB0_845:
	s_or_b64 exec, exec, s[78:79]
	v_lshlrev_b32_e32 v0, 4, v88
	v_lshl_add_u64 v[68:69], s[96:97], 0, v[0:1]
	v_lshrrev_b32_e32 v0, 2, v94
	v_or_b32_e32 v89, v95, v0
	v_lshlrev_b32_e32 v0, 3, v76
	v_and_b32_e32 v0, 24, v0
	v_add_u32_e32 v90, s68, v0
	s_waitcnt vmcnt(0) lgkmcnt(0)
	v_sub_f32_e32 v0, v22, v87
	s_lshl_b64 s[18:19], s[4:5], 15
	v_mul_f32_e32 v38, 0x3fb8aa3b, v0
	v_lshl_add_u64 v[36:37], v[68:69], 0, s[18:19]
	v_lshlrev_b32_e32 v0, 8, v94
	v_lshl_add_u64 v[34:35], v[36:37], 0, v[0:1]
	v_lshlrev_b32_e32 v104, 7, v94
	v_or_b32_e32 v0, 0x800, v104
	v_lshlrev_b32_e32 v0, 1, v0
	v_or_b32_e32 v54, 0x1000, v104
	v_lshlrev_b32_e32 v54, 1, v54
	v_or_b32_e32 v56, 0x2000, v104
	v_lshlrev_b32_e32 v56, 1, v56
	v_or_b32_e32 v58, 0x1800, v104
	v_lshlrev_b32_e32 v58, 1, v58
	v_or_b32_e32 v60, 0x2800, v104
	v_lshlrev_b32_e32 v60, 1, v60
	v_or_b32_e32 v62, 0x3000, v104
	v_lshlrev_b32_e32 v62, 1, v62
	v_or_b32_e32 v64, 0x3800, v104
	v_lshlrev_b32_e32 v64, 1, v64
	v_mov_b32_e32 v55, v1
	v_mov_b32_e32 v57, v1
	v_mov_b32_e32 v59, v1
	v_mov_b32_e32 v61, v1
	v_mov_b32_e32 v63, v1
	v_mov_b32_e32 v65, v1
	v_exp_f32_e32 v66, v38
	v_mov_b64_e32 v[118:119], v[34:35]
	global_load_dwordx4 v[18:21], v[118:119], off
	global_load_dwordx4 v[228:231], v[118:119], off offset:128
	global_load_dwordx4 v[118:121], v[118:119], off offset:64
	v_lshl_add_u64 v[122:123], v[36:37], 0, v[0:1]
	global_load_dwordx4 v[22:25], v[122:123], off
	global_load_dwordx4 v[232:235], v[122:123], off offset:128
	global_load_dwordx4 v[122:125], v[122:123], off offset:64
	v_lshl_add_u64 v[126:127], v[36:37], 0, v[54:55]
	global_load_dwordx4 v[26:29], v[126:127], off
	global_load_dwordx4 v[236:239], v[126:127], off offset:128
	global_load_dwordx4 v[126:129], v[126:127], off offset:64
	v_lshl_add_u64 v[130:131], v[36:37], 0, v[58:59]
	global_load_dwordx4 v[30:33], v[130:131], off
	global_load_dwordx4 v[240:243], v[130:131], off offset:128
	global_load_dwordx4 v[130:133], v[130:131], off offset:64
	v_lshl_add_u64 v[212:213], v[36:37], 0, v[56:57]
	global_load_dwordx4 v[248:251], v[212:213], off
	global_load_dwordx4 v[244:247], v[212:213], off offset:128
	global_load_dwordx4 v[212:215], v[212:213], off offset:64
	v_lshl_add_u64 v[216:217], v[36:37], 0, v[60:61]
	global_load_dwordx4 v[38:41], v[216:217], off
	global_load_dwordx4 v[216:219], v[216:217], off offset:64
	v_lshl_add_u64 v[220:221], v[36:37], 0, v[62:63]
	global_load_dwordx4 v[42:45], v[220:221], off
	global_load_dwordx4 v[220:223], v[220:221], off offset:64
	v_lshl_add_u64 v[224:225], v[36:37], 0, v[64:65]
	global_load_dwordx4 v[46:49], v[224:225], off
	global_load_dwordx4 v[224:227], v[224:225], off offset:64
	s_waitcnt vmcnt(20)
	v_mfma_f32_16x16x32_bf16 v[18:21], v[18:21], v[14:17], 0
	s_waitcnt vmcnt(18)
	v_mfma_f32_16x16x32_bf16 v[18:21], v[118:121], v[10:13], v[18:21]
	v_lshl_add_u64 v[118:119], v[36:37], 0, v[60:61]
	global_load_dwordx4 v[118:121], v[118:119], off offset:128
	s_waitcnt vmcnt(18)
	v_mfma_f32_16x16x32_bf16 v[22:25], v[22:25], v[14:17], 0
	s_waitcnt vmcnt(16)
	v_mfma_f32_16x16x32_bf16 v[22:25], v[122:125], v[10:13], v[22:25]
	v_lshl_add_u64 v[122:123], v[36:37], 0, v[62:63]
	global_load_dwordx4 v[122:125], v[122:123], off offset:128
	s_waitcnt vmcnt(16)
	v_mfma_f32_16x16x32_bf16 v[26:29], v[26:29], v[14:17], 0
	s_waitcnt vmcnt(14)
	v_mfma_f32_16x16x32_bf16 v[26:29], v[126:129], v[10:13], v[26:29]
	v_lshl_add_u64 v[126:127], v[36:37], 0, v[64:65]
	global_load_dwordx4 v[126:129], v[126:127], off offset:128
	s_waitcnt vmcnt(14)
	v_mfma_f32_16x16x32_bf16 v[30:33], v[30:33], v[14:17], 0
	s_waitcnt vmcnt(12)
	v_mfma_f32_16x16x32_bf16 v[30:33], v[130:133], v[10:13], v[30:33]
	v_mov_b64_e32 v[130:131], v[34:35]
	global_load_dwordx4 v[130:133], v[130:131], off offset:192
	s_waitcnt vmcnt(12)
	v_mfma_f32_16x16x32_bf16 v[248:251], v[248:251], v[14:17], 0
	s_waitcnt vmcnt(10)
	v_mfma_f32_16x16x32_bf16 v[248:251], v[212:215], v[10:13], v[248:251]
	v_lshl_add_u64 v[212:213], v[36:37], 0, v[0:1]
	global_load_dwordx4 v[212:215], v[212:213], off offset:192
	s_waitcnt vmcnt(10)
	v_mfma_f32_16x16x32_bf16 v[38:41], v[38:41], v[14:17], 0
	s_waitcnt vmcnt(9)
	v_mfma_f32_16x16x32_bf16 v[38:41], v[216:219], v[10:13], v[38:41]
	v_lshl_add_u64 v[216:217], v[36:37], 0, v[54:55]
	global_load_dwordx4 v[216:219], v[216:217], off offset:192
	s_waitcnt vmcnt(9)
	v_mfma_f32_16x16x32_bf16 v[42:45], v[42:45], v[14:17], 0
	s_waitcnt vmcnt(8)
	v_mfma_f32_16x16x32_bf16 v[42:45], v[220:223], v[10:13], v[42:45]
	v_lshl_add_u64 v[220:221], v[36:37], 0, v[58:59]
	global_load_dwordx4 v[220:223], v[220:221], off offset:192
	s_waitcnt vmcnt(8)
	v_mfma_f32_16x16x32_bf16 v[46:49], v[46:49], v[14:17], 0
	s_waitcnt vmcnt(7)
	v_mfma_f32_16x16x32_bf16 v[46:49], v[224:227], v[10:13], v[46:49]
	v_lshl_add_u64 v[224:225], v[36:37], 0, v[56:57]
	global_load_dwordx4 v[224:227], v[224:225], off offset:192
	s_waitcnt vmcnt(27)
	v_mfma_f32_16x16x32_bf16 v[18:21], v[228:231], v[6:9], v[18:21]
	v_lshl_add_u64 v[228:229], v[36:37], 0, v[60:61]
	global_load_dwordx4 v[228:231], v[228:229], off offset:192
	s_waitcnt vmcnt(25)
	v_mfma_f32_16x16x32_bf16 v[22:25], v[232:235], v[6:9], v[22:25]
	v_lshl_add_u64 v[232:233], v[36:37], 0, v[62:63]
	global_load_dwordx4 v[232:235], v[232:233], off offset:192
	s_waitcnt vmcnt(23)
	v_mfma_f32_16x16x32_bf16 v[26:29], v[236:239], v[6:9], v[26:29]
	v_lshl_add_u64 v[236:237], v[36:37], 0, v[64:65]
	global_load_dwordx4 v[236:239], v[236:237], off offset:192
	s_waitcnt vmcnt(21)
	v_mfma_f32_16x16x32_bf16 v[30:33], v[240:243], v[6:9], v[30:33]
	s_waitcnt vmcnt(18)
	v_mfma_f32_16x16x32_bf16 v[248:251], v[244:247], v[6:9], v[248:251]
	s_waitcnt vmcnt(10)
	v_mfma_f32_16x16x32_bf16 v[38:41], v[118:121], v[6:9], v[38:41]
	s_waitcnt vmcnt(9)
	v_mfma_f32_16x16x32_bf16 v[42:45], v[122:125], v[6:9], v[42:45]
	s_waitcnt vmcnt(8)
	v_mfma_f32_16x16x32_bf16 v[46:49], v[126:129], v[6:9], v[46:49]
	s_waitcnt vmcnt(7)
	v_mfma_f32_16x16x32_bf16 v[18:21], v[130:133], v[2:5], v[18:21]
	s_waitcnt vmcnt(6)
	v_mfma_f32_16x16x32_bf16 v[22:25], v[212:215], v[2:5], v[22:25]
	s_waitcnt vmcnt(5)
	v_mfma_f32_16x16x32_bf16 v[26:29], v[216:219], v[2:5], v[26:29]
	s_waitcnt vmcnt(4)
	v_mfma_f32_16x16x32_bf16 v[30:33], v[220:223], v[2:5], v[30:33]
	s_waitcnt vmcnt(3)
	v_mfma_f32_16x16x32_bf16 v[248:251], v[224:227], v[2:5], v[248:251]
	s_waitcnt vmcnt(2)
	v_mfma_f32_16x16x32_bf16 v[38:41], v[228:231], v[2:5], v[38:41]
	s_waitcnt vmcnt(1)
	v_mfma_f32_16x16x32_bf16 v[42:45], v[232:235], v[2:5], v[42:45]
	s_waitcnt vmcnt(0)
	v_mfma_f32_16x16x32_bf16 v[46:49], v[236:239], v[2:5], v[46:49]
	v_mad_u32_u24 v55, v89, s21, v90
	v_mul_f32_e32 v18, v66, v18
	v_mul_f32_e32 v19, v66, v19
	v_mul_f32_e32 v20, v66, v20
	v_mul_f32_e32 v21, v66, v21
	v_mul_f32_e32 v22, v66, v22
	v_mul_f32_e32 v23, v66, v23
	v_mul_f32_e32 v24, v66, v24
	v_mul_f32_e32 v25, v66, v25
	v_mul_f32_e32 v26, v66, v26
	v_mul_f32_e32 v27, v66, v27
	v_mul_f32_e32 v28, v66, v28
	v_mul_f32_e32 v29, v66, v29
	v_mul_f32_e32 v30, v66, v30
	v_mul_f32_e32 v31, v66, v31
	v_mul_f32_e32 v32, v66, v32
	v_mul_f32_e32 v33, v66, v33
	v_mul_f32_e32 v34, v66, v248
	v_mul_f32_e32 v35, v66, v249
	v_mul_f32_e32 v36, v66, v250
	v_mul_f32_e32 v37, v66, v251
	v_mul_f32_e32 v38, v66, v38
	v_mul_f32_e32 v39, v66, v39
	v_mul_f32_e32 v40, v66, v40
	v_mul_f32_e32 v41, v66, v41
	v_mul_f32_e32 v42, v66, v42
	v_mul_f32_e32 v43, v66, v43
	v_mul_f32_e32 v44, v66, v44
	v_mul_f32_e32 v45, v66, v45
	v_mul_f32_e32 v46, v66, v46
	v_mul_f32_e32 v47, v66, v47
	v_mul_f32_e32 v48, v66, v48
	v_mul_f32_e32 v49, v66, v49
	s_and_saveexec_b64 s[48:49], s[0:1]
	s_cbranch_execz .LBB0_849
	v_cvt_pk_bf16_f32 v72, v72, v73
	v_cvt_pk_bf16_f32 v73, v75, v74
	v_cvt_pk_bf16_f32 v74, v106, v107
	v_cvt_pk_bf16_f32 v75, v109, v108
	ds_read_b64_tr_b16 v[108:109], v55 offset:4608
	ds_read_b64_tr_b16 v[106:107], v55
	ds_read_b64_tr_b16 v[118:119], v55 offset:32
	s_waitcnt lgkmcnt(1)
	v_mfma_f32_16x16x32_bf16 v[18:21], v[106:109], v[72:75], v[18:21]
	ds_read_b64_tr_b16 v[120:121], v55 offset:4640
	ds_read_b64_tr_b16 v[106:107], v55 offset:64
	ds_read_b64_tr_b16 v[108:109], v55 offset:4672
	s_waitcnt lgkmcnt(0)
	v_mfma_f32_16x16x32_bf16 v[26:29], v[106:109], v[72:75], v[26:29]
	ds_read_b64_tr_b16 v[106:107], v55 offset:96
	ds_read_b64_tr_b16 v[108:109], v55 offset:4704
	s_waitcnt lgkmcnt(0)
	v_mfma_f32_16x16x32_bf16 v[30:33], v[106:109], v[72:75], v[30:33]
	ds_read_b64_tr_b16 v[106:107], v55 offset:128
	ds_read_b64_tr_b16 v[108:109], v55 offset:4736
	s_waitcnt lgkmcnt(0)
	v_mfma_f32_16x16x32_bf16 v[34:37], v[106:109], v[72:75], v[34:37]
	ds_read_b64_tr_b16 v[106:107], v55 offset:160
	ds_read_b64_tr_b16 v[108:109], v55 offset:4768
	s_waitcnt lgkmcnt(0)
	v_mfma_f32_16x16x32_bf16 v[38:41], v[106:109], v[72:75], v[38:41]
	ds_read_b64_tr_b16 v[106:107], v55 offset:192
	ds_read_b64_tr_b16 v[108:109], v55 offset:4800
	s_waitcnt lgkmcnt(0)
	v_mfma_f32_16x16x32_bf16 v[42:45], v[106:109], v[72:75], v[42:45]
	ds_read_b64_tr_b16 v[106:107], v55 offset:224
	ds_read_b64_tr_b16 v[108:109], v55 offset:4832
	v_mfma_f32_16x16x32_bf16 v[22:25], v[118:121], v[72:75], v[22:25]
	s_waitcnt lgkmcnt(0)
	v_mfma_f32_16x16x32_bf16 v[46:49], v[106:109], v[72:75], v[46:49]
	s_or_b64 exec, exec, s[48:49]
	s_and_saveexec_b64 s[0:1], vcc
	s_cbranch_execnz .LBB0_850
